# v46 + P0 plain conversion tiles split 17/23 between blocks with two / one ada-projection jobs
# baseline (speedup 1.0000x reference)
.Lwf_plain:
	v_and_b32_e32 v29, 63, v155
	v_lshrrev_b32_e32 v24, 6, v155
	v_lshlrev_b32_e32 v26, 2, v29
	v_lshlrev_b32_e32 v29, 1, v29
	v_readfirstlane_b32 s58, v24
	s_load_dword s6, s[0:1], 0x4c8
	s_waitcnt lgkmcnt(0)
	s_lshl_b32 s58, s58, 4
	s_cmpk_lg_u32 s6, 0x100
	s_cbranch_scc1 .Lwf_generic
	s_mov_b32 s6, 0
	s_add_i32 s7, s89, 0xfffffe80
	s_mov_b32 s30, 2
	s_cmpk_ge_i32 s7, 0x300
	s_cselect_b32 s30, 3, s30
	s_cmpk_ge_i32 s7, 0x500
	s_cselect_b32 s30, 4, s30
	s_cmpk_ge_i32 s7, 0x700
	s_cselect_b32 s30, 5, s30
	s_cmpk_ge_i32 s7, 0x900
	s_cselect_b32 s30, 6, s30
	s_cmpk_ge_i32 s7, 0xb00
	s_cselect_b32 s30, 7, s30
	s_cmpk_ge_i32 s7, 0xd00
	s_cselect_b32 s30, 8, s30
	s_cmpk_ge_i32 s7, 0xf00
	s_cselect_b32 s30, 9, s30
	s_cmpk_ge_i32 s7, 0x1100
	s_cselect_b32 s30, 10, s30
	s_cmpk_ge_i32 s7, 0x1280
	s_cselect_b32 s30, 11, s30
	s_cmpk_ge_i32 s7, 0x1400
	s_cselect_b32 s30, 12, s30
	s_cmpk_ge_i32 s7, 0x1480
	s_cselect_b32 s30, 13, s30
	s_mul_i32 s59, s30, 48
	s_add_u32 s10, s0, s59
	s_addc_u32 s11, s1, 0
	s_load_dwordx2 s[50:51], s[10:11], 0x100
	s_load_dwordx2 s[52:53], s[10:11], 0x110
	s_load_dwordx2 s[90:91], s[10:11], 0x118
	s_load_dword s30, s[10:11], 0x128
	s_load_dwordx2 vcc, s[0:1], 0xf8
	s_waitcnt lgkmcnt(0)
	s_sub_i32 s7, s7, s30
	s_lshr_b32 s59, s90, 7
	s_add_i32 s10, s59, -1
	s_and_b32 s10, s7, s10
	s_ff1_i32_b32 s59, s59
	s_lshr_b32 s7, s7, s59
	s_lshl_b32 s10, s10, 7
	s_add_i32 s10, s10, s58
	s_lshl_b32 s11, s7, 6
	s_mul_i32 s59, s10, s91
	s_add_i32 s59, s59, s11
	s_lshl_b32 s59, s59, 2
	s_add_u32 s50, s50, s59
	s_addc_u32 s51, s51, 0
	s_mul_i32 s59, s11, s90
	s_add_i32 s59, s59, s10
	s_lshl_b32 s59, s59, 1
	s_add_u32 s52, s52, s59
	s_addc_u32 s53, s53, 0
	s_add_u32 s52, s52, vcc_lo
	s_addc_u32 s53, s53, vcc_hi
	v_mul_u32_u24_e32 v27, s90, v29
	s_lshl_b32 s91, s91, 2
	global_load_dword v0, v26, s[50:51] nt
	s_add_u32 s50, s50, s91
	s_addc_u32 s51, s51, 0
	global_load_dword v1, v26, s[50:51] nt
	s_add_u32 s50, s50, s91
	s_addc_u32 s51, s51, 0
	global_load_dword v2, v26, s[50:51] nt
	s_add_u32 s50, s50, s91
	s_addc_u32 s51, s51, 0
	global_load_dword v3, v26, s[50:51] nt
	s_add_u32 s50, s50, s91
	s_addc_u32 s51, s51, 0
	global_load_dword v4, v26, s[50:51] nt
	s_add_u32 s50, s50, s91
	s_addc_u32 s51, s51, 0
	global_load_dword v5, v26, s[50:51] nt
	s_add_u32 s50, s50, s91
	s_addc_u32 s51, s51, 0
	global_load_dword v6, v26, s[50:51] nt
	s_add_u32 s50, s50, s91
	s_addc_u32 s51, s51, 0
	global_load_dword v7, v26, s[50:51] nt
	s_add_u32 s50, s50, s91
	s_addc_u32 s51, s51, 0
	global_load_dword v8, v26, s[50:51] nt
	s_add_u32 s50, s50, s91
	s_addc_u32 s51, s51, 0
	global_load_dword v9, v26, s[50:51] nt
	s_add_u32 s50, s50, s91
	s_addc_u32 s51, s51, 0
	global_load_dword v10, v26, s[50:51] nt
	s_add_u32 s50, s50, s91
	s_addc_u32 s51, s51, 0
	global_load_dword v11, v26, s[50:51] nt
	s_add_u32 s50, s50, s91
	s_addc_u32 s51, s51, 0
	global_load_dword v12, v26, s[50:51] nt
	s_add_u32 s50, s50, s91
	s_addc_u32 s51, s51, 0
	global_load_dword v13, v26, s[50:51] nt
	s_add_u32 s50, s50, s91
	s_addc_u32 s51, s51, 0
	global_load_dword v14, v26, s[50:51] nt
	s_add_u32 s50, s50, s91
	s_addc_u32 s51, s51, 0
	global_load_dword v15, v26, s[50:51] nt
	s_add_i32 s6, s6, 1
	s_cmp_ge_u32 s92, 0x80
	s_cselect_b32 s7, 23, 17
	s_cmp_ge_u32 s6, s7
	s_cbranch_scc1 .Lwf_pdrain1
	s_add_i32 s7, s92, 0x80
	s_and_b32 s7, s7, 0xff
	s_lshl_b32 s89, s6, 8
	s_add_i32 s89, s89, s7
	s_addk_i32 s89, 0x280
	s_lshl_b32 s7, s6, 7
	s_add_i32 s7, s7, s92
	s_addk_i32 s7, 0xa80
	s_cmp_ge_u32 s6, 17
	s_cselect_b32 s89, s7, s89
	s_add_i32 s7, s89, 0xfffffe80
	s_mov_b32 s30, 2
	s_cmpk_ge_i32 s7, 0x300
	s_cselect_b32 s30, 3, s30
	s_cmpk_ge_i32 s7, 0x500
	s_cselect_b32 s30, 4, s30
	s_cmpk_ge_i32 s7, 0x700
	s_cselect_b32 s30, 5, s30
	s_cmpk_ge_i32 s7, 0x900
	s_cselect_b32 s30, 6, s30
	s_cmpk_ge_i32 s7, 0xb00
	s_cselect_b32 s30, 7, s30
	s_cmpk_ge_i32 s7, 0xd00
	s_cselect_b32 s30, 8, s30
	s_cmpk_ge_i32 s7, 0xf00
	s_cselect_b32 s30, 9, s30
	s_cmpk_ge_i32 s7, 0x1100
	s_cselect_b32 s30, 10, s30
	s_cmpk_ge_i32 s7, 0x1280
	s_cselect_b32 s30, 11, s30
	s_cmpk_ge_i32 s7, 0x1400
	s_cselect_b32 s30, 12, s30
	s_cmpk_ge_i32 s7, 0x1480
	s_cselect_b32 s30, 13, s30
	s_mul_i32 s59, s30, 48
	s_add_u32 s10, s0, s59
	s_addc_u32 s11, s1, 0
	s_load_dwordx2 s[50:51], s[10:11], 0x100
	s_load_dwordx2 s[54:55], s[10:11], 0x110
	s_load_dwordx2 s[90:91], s[10:11], 0x118
	s_load_dword s30, s[10:11], 0x128
	s_load_dwordx2 vcc, s[0:1], 0xf8
	s_waitcnt lgkmcnt(0)
	s_sub_i32 s7, s7, s30
	s_lshr_b32 s59, s90, 7
	s_add_i32 s10, s59, -1
	s_and_b32 s10, s7, s10
	s_ff1_i32_b32 s59, s59
	s_lshr_b32 s7, s7, s59
	s_lshl_b32 s10, s10, 7
	s_add_i32 s10, s10, s58
	s_lshl_b32 s11, s7, 6
	s_mul_i32 s59, s10, s91
	s_add_i32 s59, s59, s11
	s_lshl_b32 s59, s59, 2
	s_add_u32 s50, s50, s59
	s_addc_u32 s51, s51, 0
	s_mul_i32 s59, s11, s90
	s_add_i32 s59, s59, s10
	s_lshl_b32 s59, s59, 1
	s_add_u32 s54, s54, s59
	s_addc_u32 s55, s55, 0
	s_add_u32 s54, s54, vcc_lo
	s_addc_u32 s55, s55, vcc_hi
	v_mul_u32_u24_e32 v28, s90, v29
	s_lshl_b32 s91, s91, 2
	global_load_dword v30, v26, s[50:51] nt
	s_add_u32 s50, s50, s91
	s_addc_u32 s51, s51, 0
	global_load_dword v31, v26, s[50:51] nt
	s_add_u32 s50, s50, s91
	s_addc_u32 s51, s51, 0
	global_load_dword v32, v26, s[50:51] nt
	s_add_u32 s50, s50, s91
	s_addc_u32 s51, s51, 0
	global_load_dword v33, v26, s[50:51] nt
	s_add_u32 s50, s50, s91
	s_addc_u32 s51, s51, 0
	global_load_dword v34, v26, s[50:51] nt
	s_add_u32 s50, s50, s91
	s_addc_u32 s51, s51, 0
	global_load_dword v35, v26, s[50:51] nt
	s_add_u32 s50, s50, s91
	s_addc_u32 s51, s51, 0
	global_load_dword v36, v26, s[50:51] nt
	s_add_u32 s50, s50, s91
	s_addc_u32 s51, s51, 0
	global_load_dword v37, v26, s[50:51] nt
	s_add_u32 s50, s50, s91
	s_addc_u32 s51, s51, 0
	global_load_dword v38, v26, s[50:51] nt
	s_add_u32 s50, s50, s91
	s_addc_u32 s51, s51, 0
	global_load_dword v39, v26, s[50:51] nt
	s_add_u32 s50, s50, s91
	s_addc_u32 s51, s51, 0
	global_load_dword v40, v26, s[50:51] nt
	s_add_u32 s50, s50, s91
	s_addc_u32 s51, s51, 0
	global_load_dword v41, v26, s[50:51] nt
	s_add_u32 s50, s50, s91
	s_addc_u32 s51, s51, 0
	global_load_dword v42, v26, s[50:51] nt
	s_add_u32 s50, s50, s91
	s_addc_u32 s51, s51, 0
	global_load_dword v43, v26, s[50:51] nt
	s_add_u32 s50, s50, s91
	s_addc_u32 s51, s51, 0
	global_load_dword v44, v26, s[50:51] nt
	s_add_u32 s50, s50, s91
	s_addc_u32 s51, s51, 0
	global_load_dword v45, v26, s[50:51] nt
	s_add_i32 s6, s6, 1
	s_cmp_ge_u32 s92, 0x80
	s_cselect_b32 s7, 23, 17
	s_cmp_ge_u32 s6, s7
	s_cbranch_scc1 .Lwf_pdrain2
	s_add_i32 s7, s92, 0x80
	s_and_b32 s7, s7, 0xff
	s_lshl_b32 s89, s6, 8
	s_add_i32 s89, s89, s7
	s_addk_i32 s89, 0x280
	s_lshl_b32 s7, s6, 7
	s_add_i32 s7, s7, s92
	s_addk_i32 s7, 0xa80
	s_cmp_ge_u32 s6, 17
	s_cselect_b32 s89, s7, s89
	s_add_i32 s7, s89, 0xfffffe80
	s_mov_b32 s30, 2
	s_cmpk_ge_i32 s7, 0x300
	s_cselect_b32 s30, 3, s30
	s_cmpk_ge_i32 s7, 0x500
	s_cselect_b32 s30, 4, s30
	s_cmpk_ge_i32 s7, 0x700
	s_cselect_b32 s30, 5, s30
	s_cmpk_ge_i32 s7, 0x900
	s_cselect_b32 s30, 6, s30
	s_cmpk_ge_i32 s7, 0xb00
	s_cselect_b32 s30, 7, s30
	s_cmpk_ge_i32 s7, 0xd00
	s_cselect_b32 s30, 8, s30
	s_cmpk_ge_i32 s7, 0xf00
	s_cselect_b32 s30, 9, s30
	s_cmpk_ge_i32 s7, 0x1100
	s_cselect_b32 s30, 10, s30
	s_cmpk_ge_i32 s7, 0x1280
	s_cselect_b32 s30, 11, s30
	s_cmpk_ge_i32 s7, 0x1400
	s_cselect_b32 s30, 12, s30
	s_cmpk_ge_i32 s7, 0x1480
	s_cselect_b32 s30, 13, s30
	s_mul_i32 s59, s30, 48
	s_add_u32 s10, s0, s59
	s_addc_u32 s11, s1, 0
	s_load_dwordx2 s[50:51], s[10:11], 0x100
	s_load_dwordx2 s[56:57], s[10:11], 0x110
	s_load_dwordx2 s[90:91], s[10:11], 0x118
	s_load_dword s30, s[10:11], 0x128
	s_load_dwordx2 vcc, s[0:1], 0xf8
	s_waitcnt lgkmcnt(0)
	s_sub_i32 s7, s7, s30
	s_lshr_b32 s59, s90, 7
	s_add_i32 s10, s59, -1
	s_and_b32 s10, s7, s10
	s_ff1_i32_b32 s59, s59
	s_lshr_b32 s7, s7, s59
	s_lshl_b32 s10, s10, 7
	s_add_i32 s10, s10, s58
	s_lshl_b32 s11, s7, 6
	s_mul_i32 s59, s10, s91
	s_add_i32 s59, s59, s11
	s_lshl_b32 s59, s59, 2
	s_add_u32 s50, s50, s59
	s_addc_u32 s51, s51, 0
	s_mul_i32 s59, s11, s90
	s_add_i32 s59, s59, s10
	s_lshl_b32 s59, s59, 1
	s_add_u32 s56, s56, s59
	s_addc_u32 s57, s57, 0
	s_add_u32 s56, s56, vcc_lo
	s_addc_u32 s57, s57, vcc_hi
	v_mul_u32_u24_e32 v78, s90, v29
	s_lshl_b32 s91, s91, 2
	global_load_dword v46, v26, s[50:51] nt
	s_add_u32 s50, s50, s91
	s_addc_u32 s51, s51, 0
	global_load_dword v47, v26, s[50:51] nt
	s_add_u32 s50, s50, s91
	s_addc_u32 s51, s51, 0
	global_load_dword v48, v26, s[50:51] nt
	s_add_u32 s50, s50, s91
	s_addc_u32 s51, s51, 0
	global_load_dword v49, v26, s[50:51] nt
	s_add_u32 s50, s50, s91
	s_addc_u32 s51, s51, 0
	global_load_dword v50, v26, s[50:51] nt
	s_add_u32 s50, s50, s91
	s_addc_u32 s51, s51, 0
	global_load_dword v51, v26, s[50:51] nt
	s_add_u32 s50, s50, s91
	s_addc_u32 s51, s51, 0
	global_load_dword v52, v26, s[50:51] nt
	s_add_u32 s50, s50, s91
	s_addc_u32 s51, s51, 0
	global_load_dword v53, v26, s[50:51] nt
	s_add_u32 s50, s50, s91
	s_addc_u32 s51, s51, 0
	global_load_dword v54, v26, s[50:51] nt
	s_add_u32 s50, s50, s91
	s_addc_u32 s51, s51, 0
	global_load_dword v55, v26, s[50:51] nt
	s_add_u32 s50, s50, s91
	s_addc_u32 s51, s51, 0
	global_load_dword v56, v26, s[50:51] nt
	s_add_u32 s50, s50, s91
	s_addc_u32 s51, s51, 0
	global_load_dword v57, v26, s[50:51] nt
	s_add_u32 s50, s50, s91
	s_addc_u32 s51, s51, 0
	global_load_dword v58, v26, s[50:51] nt
	s_add_u32 s50, s50, s91
	s_addc_u32 s51, s51, 0
	global_load_dword v59, v26, s[50:51] nt
	s_add_u32 s50, s50, s91
	s_addc_u32 s51, s51, 0
	global_load_dword v60, v26, s[50:51] nt
	s_add_u32 s50, s50, s91
	s_addc_u32 s51, s51, 0
	global_load_dword v61, v26, s[50:51] nt
.Lwf_loop:
	s_waitcnt vmcnt(32)
	v_cvt_pk_bf16_f32 v0, v0, v1
	v_cvt_pk_bf16_f32 v1, v2, v3
	v_cvt_pk_bf16_f32 v2, v4, v5
	v_cvt_pk_bf16_f32 v3, v6, v7
	v_cvt_pk_bf16_f32 v4, v8, v9
	v_cvt_pk_bf16_f32 v5, v10, v11
	v_cvt_pk_bf16_f32 v6, v12, v13
	v_cvt_pk_bf16_f32 v7, v14, v15
	global_store_dwordx4 v27, v[0:3], s[52:53]
	global_store_dwordx4 v27, v[4:7], s[52:53] offset:16
	s_add_i32 s6, s6, 1
	s_cmp_ge_u32 s92, 0x80
	s_cselect_b32 s7, 23, 17
	s_cmp_ge_u32 s6, s7
	s_cbranch_scc1 .Lwf_drain0
	s_add_i32 s7, s92, 0x80
	s_and_b32 s7, s7, 0xff
	s_lshl_b32 s89, s6, 8
	s_add_i32 s89, s89, s7
	s_addk_i32 s89, 0x280
	s_lshl_b32 s7, s6, 7
	s_add_i32 s7, s7, s92
	s_addk_i32 s7, 0xa80
	s_cmp_ge_u32 s6, 17
	s_cselect_b32 s89, s7, s89
	s_add_i32 s7, s89, 0xfffffe80
	s_mov_b32 s30, 2
	s_cmpk_ge_i32 s7, 0x300
	s_cselect_b32 s30, 3, s30
	s_cmpk_ge_i32 s7, 0x500
	s_cselect_b32 s30, 4, s30
	s_cmpk_ge_i32 s7, 0x700
	s_cselect_b32 s30, 5, s30
	s_cmpk_ge_i32 s7, 0x900
	s_cselect_b32 s30, 6, s30
	s_cmpk_ge_i32 s7, 0xb00
	s_cselect_b32 s30, 7, s30
	s_cmpk_ge_i32 s7, 0xd00
	s_cselect_b32 s30, 8, s30
	s_cmpk_ge_i32 s7, 0xf00
	s_cselect_b32 s30, 9, s30
	s_cmpk_ge_i32 s7, 0x1100
	s_cselect_b32 s30, 10, s30
	s_cmpk_ge_i32 s7, 0x1280
	s_cselect_b32 s30, 11, s30
	s_cmpk_ge_i32 s7, 0x1400
	s_cselect_b32 s30, 12, s30
	s_cmpk_ge_i32 s7, 0x1480
	s_cselect_b32 s30, 13, s30
	s_mul_i32 s59, s30, 48
	s_add_u32 s10, s0, s59
	s_addc_u32 s11, s1, 0
	s_load_dwordx2 s[50:51], s[10:11], 0x100
	s_load_dwordx2 s[52:53], s[10:11], 0x110
	s_load_dwordx2 s[90:91], s[10:11], 0x118
	s_load_dword s30, s[10:11], 0x128
	s_load_dwordx2 vcc, s[0:1], 0xf8
	s_waitcnt lgkmcnt(0)
	s_sub_i32 s7, s7, s30
	s_lshr_b32 s59, s90, 7
	s_add_i32 s10, s59, -1
	s_and_b32 s10, s7, s10
	s_ff1_i32_b32 s59, s59
	s_lshr_b32 s7, s7, s59
	s_lshl_b32 s10, s10, 7
	s_add_i32 s10, s10, s58
	s_lshl_b32 s11, s7, 6
	s_mul_i32 s59, s10, s91
	s_add_i32 s59, s59, s11
	s_lshl_b32 s59, s59, 2
	s_add_u32 s50, s50, s59
	s_addc_u32 s51, s51, 0
	s_mul_i32 s59, s11, s90
	s_add_i32 s59, s59, s10
	s_lshl_b32 s59, s59, 1
	s_add_u32 s52, s52, s59
	s_addc_u32 s53, s53, 0
	s_add_u32 s52, s52, vcc_lo
	s_addc_u32 s53, s53, vcc_hi
	v_mul_u32_u24_e32 v27, s90, v29
	s_lshl_b32 s91, s91, 2
	global_load_dword v0, v26, s[50:51] nt
	s_add_u32 s50, s50, s91
	s_addc_u32 s51, s51, 0
	global_load_dword v1, v26, s[50:51] nt
	s_add_u32 s50, s50, s91
	s_addc_u32 s51, s51, 0
	global_load_dword v2, v26, s[50:51] nt
	s_add_u32 s50, s50, s91
	s_addc_u32 s51, s51, 0
	global_load_dword v3, v26, s[50:51] nt
	s_add_u32 s50, s50, s91
	s_addc_u32 s51, s51, 0
	global_load_dword v4, v26, s[50:51] nt
	s_add_u32 s50, s50, s91
	s_addc_u32 s51, s51, 0
	global_load_dword v5, v26, s[50:51] nt
	s_add_u32 s50, s50, s91
	s_addc_u32 s51, s51, 0
	global_load_dword v6, v26, s[50:51] nt
	s_add_u32 s50, s50, s91
	s_addc_u32 s51, s51, 0
	global_load_dword v7, v26, s[50:51] nt
	s_add_u32 s50, s50, s91
	s_addc_u32 s51, s51, 0
	global_load_dword v8, v26, s[50:51] nt
	s_add_u32 s50, s50, s91
	s_addc_u32 s51, s51, 0
	global_load_dword v9, v26, s[50:51] nt
	s_add_u32 s50, s50, s91
	s_addc_u32 s51, s51, 0
	global_load_dword v10, v26, s[50:51] nt
	s_add_u32 s50, s50, s91
	s_addc_u32 s51, s51, 0
	global_load_dword v11, v26, s[50:51] nt
	s_add_u32 s50, s50, s91
	s_addc_u32 s51, s51, 0
	global_load_dword v12, v26, s[50:51] nt
	s_add_u32 s50, s50, s91
	s_addc_u32 s51, s51, 0
	global_load_dword v13, v26, s[50:51] nt
	s_add_u32 s50, s50, s91
	s_addc_u32 s51, s51, 0
	global_load_dword v14, v26, s[50:51] nt
	s_add_u32 s50, s50, s91
	s_addc_u32 s51, s51, 0
	global_load_dword v15, v26, s[50:51] nt
	s_waitcnt vmcnt(32)
	v_cvt_pk_bf16_f32 v30, v30, v31
	v_cvt_pk_bf16_f32 v31, v32, v33
	v_cvt_pk_bf16_f32 v32, v34, v35
	v_cvt_pk_bf16_f32 v33, v36, v37
	v_cvt_pk_bf16_f32 v34, v38, v39
	v_cvt_pk_bf16_f32 v35, v40, v41
	v_cvt_pk_bf16_f32 v36, v42, v43
	v_cvt_pk_bf16_f32 v37, v44, v45
	global_store_dwordx4 v28, v[30:33], s[54:55]
	global_store_dwordx4 v28, v[34:37], s[54:55] offset:16
	s_add_i32 s6, s6, 1
	s_cmp_ge_u32 s92, 0x80
	s_cselect_b32 s7, 23, 17
	s_cmp_ge_u32 s6, s7
	s_cbranch_scc1 .Lwf_drain1
	s_add_i32 s7, s92, 0x80
	s_and_b32 s7, s7, 0xff
	s_lshl_b32 s89, s6, 8
	s_add_i32 s89, s89, s7
	s_addk_i32 s89, 0x280
	s_lshl_b32 s7, s6, 7
	s_add_i32 s7, s7, s92
	s_addk_i32 s7, 0xa80
	s_cmp_ge_u32 s6, 17
	s_cselect_b32 s89, s7, s89
	s_add_i32 s7, s89, 0xfffffe80
	s_mov_b32 s30, 2
	s_cmpk_ge_i32 s7, 0x300
	s_cselect_b32 s30, 3, s30
	s_cmpk_ge_i32 s7, 0x500
	s_cselect_b32 s30, 4, s30
	s_cmpk_ge_i32 s7, 0x700
	s_cselect_b32 s30, 5, s30
	s_cmpk_ge_i32 s7, 0x900
	s_cselect_b32 s30, 6, s30
	s_cmpk_ge_i32 s7, 0xb00
	s_cselect_b32 s30, 7, s30
	s_cmpk_ge_i32 s7, 0xd00
	s_cselect_b32 s30, 8, s30
	s_cmpk_ge_i32 s7, 0xf00
	s_cselect_b32 s30, 9, s30
	s_cmpk_ge_i32 s7, 0x1100
	s_cselect_b32 s30, 10, s30
	s_cmpk_ge_i32 s7, 0x1280
	s_cselect_b32 s30, 11, s30
	s_cmpk_ge_i32 s7, 0x1400
	s_cselect_b32 s30, 12, s30
	s_cmpk_ge_i32 s7, 0x1480
	s_cselect_b32 s30, 13, s30
	s_mul_i32 s59, s30, 48
	s_add_u32 s10, s0, s59
	s_addc_u32 s11, s1, 0
	s_load_dwordx2 s[50:51], s[10:11], 0x100
	s_load_dwordx2 s[54:55], s[10:11], 0x110
	s_load_dwordx2 s[90:91], s[10:11], 0x118
	s_load_dword s30, s[10:11], 0x128
	s_load_dwordx2 vcc, s[0:1], 0xf8
	s_waitcnt lgkmcnt(0)
	s_sub_i32 s7, s7, s30
	s_lshr_b32 s59, s90, 7
	s_add_i32 s10, s59, -1
	s_and_b32 s10, s7, s10
	s_ff1_i32_b32 s59, s59
	s_lshr_b32 s7, s7, s59
	s_lshl_b32 s10, s10, 7
	s_add_i32 s10, s10, s58
	s_lshl_b32 s11, s7, 6
	s_mul_i32 s59, s10, s91
	s_add_i32 s59, s59, s11
	s_lshl_b32 s59, s59, 2
	s_add_u32 s50, s50, s59
	s_addc_u32 s51, s51, 0
	s_mul_i32 s59, s11, s90
	s_add_i32 s59, s59, s10
	s_lshl_b32 s59, s59, 1
	s_add_u32 s54, s54, s59
	s_addc_u32 s55, s55, 0
	s_add_u32 s54, s54, vcc_lo
	s_addc_u32 s55, s55, vcc_hi
	v_mul_u32_u24_e32 v28, s90, v29
	s_lshl_b32 s91, s91, 2
	global_load_dword v30, v26, s[50:51] nt
	s_add_u32 s50, s50, s91
	s_addc_u32 s51, s51, 0
	global_load_dword v31, v26, s[50:51] nt
	s_add_u32 s50, s50, s91
	s_addc_u32 s51, s51, 0
	global_load_dword v32, v26, s[50:51] nt
	s_add_u32 s50, s50, s91
	s_addc_u32 s51, s51, 0
	global_load_dword v33, v26, s[50:51] nt
	s_add_u32 s50, s50, s91
	s_addc_u32 s51, s51, 0
	global_load_dword v34, v26, s[50:51] nt
	s_add_u32 s50, s50, s91
	s_addc_u32 s51, s51, 0
	global_load_dword v35, v26, s[50:51] nt
	s_add_u32 s50, s50, s91
	s_addc_u32 s51, s51, 0
	global_load_dword v36, v26, s[50:51] nt
	s_add_u32 s50, s50, s91
	s_addc_u32 s51, s51, 0
	global_load_dword v37, v26, s[50:51] nt
	s_add_u32 s50, s50, s91
	s_addc_u32 s51, s51, 0
	global_load_dword v38, v26, s[50:51] nt
	s_add_u32 s50, s50, s91
	s_addc_u32 s51, s51, 0
	global_load_dword v39, v26, s[50:51] nt
	s_add_u32 s50, s50, s91
	s_addc_u32 s51, s51, 0
	global_load_dword v40, v26, s[50:51] nt
	s_add_u32 s50, s50, s91
	s_addc_u32 s51, s51, 0
	global_load_dword v41, v26, s[50:51] nt
	s_add_u32 s50, s50, s91
	s_addc_u32 s51, s51, 0
	global_load_dword v42, v26, s[50:51] nt
	s_add_u32 s50, s50, s91
	s_addc_u32 s51, s51, 0
	global_load_dword v43, v26, s[50:51] nt
	s_add_u32 s50, s50, s91
	s_addc_u32 s51, s51, 0
	global_load_dword v44, v26, s[50:51] nt
	s_add_u32 s50, s50, s91
	s_addc_u32 s51, s51, 0
	global_load_dword v45, v26, s[50:51] nt
	s_waitcnt vmcnt(32)
	v_cvt_pk_bf16_f32 v46, v46, v47
	v_cvt_pk_bf16_f32 v47, v48, v49
	v_cvt_pk_bf16_f32 v48, v50, v51
	v_cvt_pk_bf16_f32 v49, v52, v53
	v_cvt_pk_bf16_f32 v50, v54, v55
	v_cvt_pk_bf16_f32 v51, v56, v57
	v_cvt_pk_bf16_f32 v52, v58, v59
	v_cvt_pk_bf16_f32 v53, v60, v61
	global_store_dwordx4 v78, v[46:49], s[56:57]
	global_store_dwordx4 v78, v[50:53], s[56:57] offset:16
	s_add_i32 s6, s6, 1
	s_cmp_ge_u32 s92, 0x80
	s_cselect_b32 s7, 23, 17
	s_cmp_ge_u32 s6, s7
	s_cbranch_scc1 .Lwf_drain2
	s_add_i32 s7, s92, 0x80
	s_and_b32 s7, s7, 0xff
	s_lshl_b32 s89, s6, 8
	s_add_i32 s89, s89, s7
	s_addk_i32 s89, 0x280
	s_lshl_b32 s7, s6, 7
	s_add_i32 s7, s7, s92
	s_addk_i32 s7, 0xa80
	s_cmp_ge_u32 s6, 17
	s_cselect_b32 s89, s7, s89
	s_add_i32 s7, s89, 0xfffffe80
	s_mov_b32 s30, 2
	s_cmpk_ge_i32 s7, 0x300
	s_cselect_b32 s30, 3, s30
	s_cmpk_ge_i32 s7, 0x500
	s_cselect_b32 s30, 4, s30
	s_cmpk_ge_i32 s7, 0x700
	s_cselect_b32 s30, 5, s30
	s_cmpk_ge_i32 s7, 0x900
	s_cselect_b32 s30, 6, s30
	s_cmpk_ge_i32 s7, 0xb00
	s_cselect_b32 s30, 7, s30
	s_cmpk_ge_i32 s7, 0xd00
	s_cselect_b32 s30, 8, s30
	s_cmpk_ge_i32 s7, 0xf00
	s_cselect_b32 s30, 9, s30
	s_cmpk_ge_i32 s7, 0x1100
	s_cselect_b32 s30, 10, s30
	s_cmpk_ge_i32 s7, 0x1280
	s_cselect_b32 s30, 11, s30
	s_cmpk_ge_i32 s7, 0x1400
	s_cselect_b32 s30, 12, s30
	s_cmpk_ge_i32 s7, 0x1480
	s_cselect_b32 s30, 13, s30
	s_mul_i32 s59, s30, 48
	s_add_u32 s10, s0, s59
	s_addc_u32 s11, s1, 0
	s_load_dwordx2 s[50:51], s[10:11], 0x100
	s_load_dwordx2 s[56:57], s[10:11], 0x110
	s_load_dwordx2 s[90:91], s[10:11], 0x118
	s_load_dword s30, s[10:11], 0x128
	s_load_dwordx2 vcc, s[0:1], 0xf8
	s_waitcnt lgkmcnt(0)
	s_sub_i32 s7, s7, s30
	s_lshr_b32 s59, s90, 7
	s_add_i32 s10, s59, -1
	s_and_b32 s10, s7, s10
	s_ff1_i32_b32 s59, s59
	s_lshr_b32 s7, s7, s59
	s_lshl_b32 s10, s10, 7
	s_add_i32 s10, s10, s58
	s_lshl_b32 s11, s7, 6
	s_mul_i32 s59, s10, s91
	s_add_i32 s59, s59, s11
	s_lshl_b32 s59, s59, 2
	s_add_u32 s50, s50, s59
	s_addc_u32 s51, s51, 0
	s_mul_i32 s59, s11, s90
	s_add_i32 s59, s59, s10
	s_lshl_b32 s59, s59, 1
	s_add_u32 s56, s56, s59
	s_addc_u32 s57, s57, 0
	s_add_u32 s56, s56, vcc_lo
	s_addc_u32 s57, s57, vcc_hi
	v_mul_u32_u24_e32 v78, s90, v29
	s_lshl_b32 s91, s91, 2
	global_load_dword v46, v26, s[50:51] nt
	s_add_u32 s50, s50, s91
	s_addc_u32 s51, s51, 0
	global_load_dword v47, v26, s[50:51] nt
	s_add_u32 s50, s50, s91
	s_addc_u32 s51, s51, 0
	global_load_dword v48, v26, s[50:51] nt
	s_add_u32 s50, s50, s91
	s_addc_u32 s51, s51, 0
	global_load_dword v49, v26, s[50:51] nt
	s_add_u32 s50, s50, s91
	s_addc_u32 s51, s51, 0
	global_load_dword v50, v26, s[50:51] nt
	s_add_u32 s50, s50, s91
	s_addc_u32 s51, s51, 0
	global_load_dword v51, v26, s[50:51] nt
	s_add_u32 s50, s50, s91
	s_addc_u32 s51, s51, 0
	global_load_dword v52, v26, s[50:51] nt
	s_add_u32 s50, s50, s91
	s_addc_u32 s51, s51, 0
	global_load_dword v53, v26, s[50:51] nt
	s_add_u32 s50, s50, s91
	s_addc_u32 s51, s51, 0
	global_load_dword v54, v26, s[50:51] nt
	s_add_u32 s50, s50, s91
	s_addc_u32 s51, s51, 0
	global_load_dword v55, v26, s[50:51] nt
	s_add_u32 s50, s50, s91
	s_addc_u32 s51, s51, 0
	global_load_dword v56, v26, s[50:51] nt
	s_add_u32 s50, s50, s91
	s_addc_u32 s51, s51, 0
	global_load_dword v57, v26, s[50:51] nt
	s_add_u32 s50, s50, s91
	s_addc_u32 s51, s51, 0
	global_load_dword v58, v26, s[50:51] nt
	s_add_u32 s50, s50, s91
	s_addc_u32 s51, s51, 0
	global_load_dword v59, v26, s[50:51] nt
	s_add_u32 s50, s50, s91
	s_addc_u32 s51, s51, 0
	global_load_dword v60, v26, s[50:51] nt
	s_add_u32 s50, s50, s91
	s_addc_u32 s51, s51, 0
	global_load_dword v61, v26, s[50:51] nt
	s_branch .Lwf_loop

.Lwf_done:
	s_cmp_ge_u32 s92, 0x80
	s_movk_i32 s7, 0x1700
	s_cselect_b32 s89, 0x1600, s7
	s_add_i32 s89, s89, s92
	s_cmp_ge_i32 s89, s62
	s_cbranch_scc1 .LBB0_113
